# P6: stagger the two wave-halves' tile epilogues (alignment barriers only on the last tile) so each epilogue runs beside the other half's MFMA segment
# speedup vs baseline: 1.0014x; 1.0014x over previous
; #define PG8_STAGE(bufoff, gbase, voff) do { _Pragma("unroll") for (int _i = 0; _i < 2; ++_i) \
;         __builtin_amdgcn_global_load_lds((const unsigned*)((const char*)(gbase) + (voff)[_i]), (LAS unsigned*)(lds + (bufoff) + ldsw + _i * 8192), 16, 0, 0); } while (0)
; #define PG8_LDA(dst, b, h) do { _Pragma("unroll") for (int m = 0; m < 4; ++m) _Pragma("unroll") for (int k = 0; k < 2; ++k) dst[m][k] = *(const LAS bf16x8*)(lds + PG8_SA(b, h) + aoff + m * 2048 + k * 1024); } while (0)
; #define PG8_LDB(dst, b, h) do { _Pragma("unroll") for (int n = 0; n < 2; ++n) _Pragma("unroll") for (int k = 0; k < 2; ++k) dst[n][k] = *(const LAS bf16x8*)(lds + PG8_SB(b, h) + boff + n * 2048 + k * 1024); } while (0)
; #define PG8_WAIT_V(n) asm volatile("s_waitcnt vmcnt(" #n ")" ::: "memory")
; #define PG8_BAR __builtin_amdgcn_s_barrier()
; template <class Epi, class Sched>
; __device__ __forceinline__ void gemm_phase(LAS unsigned char* lds, const Gemm g, const Sched& S, const Epi& E, int tid_in) {
;     ...
;         for (int t = 0; t < nt; t += 2) {
;             const bool last = (t == nt - 2);
;             const char* a1 = cA + (size_t)(t + 1) * kstep;
;             const char* a2 = last ? nA : cA + (size_t)(t + 2) * kstep; const char* b2 = last ? nB : cB + (size_t)(t + 2) * kstep;
;             const char* a3 = a2 + kstep; const char* b3 = b2 + kstep;
;             PG8_LDB(B0, 0, 0); PG8_LDB(B1, 0, 1); PG8_SCHED; PG8_LDA(At, 0, 0); PG8_STAGE(PG8_SA(1, 0), a1, voffA); PG8_STAGE(PG8_SA(1, 1), a1 + hstep, voffA);
;             PG8_WAIT_V(8); PG8_WAIT_L(0); PG8_BAR; PG8_MMA(0, 0, At, B0); PG8_MMA(0, 1, At, B1); PG8_BAR; PG8_SCHED;
;             PG8_LDA(At, 0, 1); PG8_STAGE(PG8_SB(0, 0), b2, voffB); PG8_STAGE(PG8_SB(0, 1), b2 + hstep, voffB);
;             PG8_WAIT_V(6); PG8_WAIT_L(0); PG8_BAR; PG8_MMA(1, 0, At, B0); PG8_MMA(1, 1, At, B1); PG8_BAR; PG8_SCHED;
;             PG8_LDB(B0, 1, 0); PG8_LDB(B1, 1, 1); PG8_SCHED; PG8_LDA(At, 1, 0); PG8_STAGE(PG8_SA(0, 0), a2, voffA); PG8_STAGE(PG8_SA(0, 1), a2 + hstep, voffA);
;             PG8_WAIT_V(8); PG8_WAIT_L(0); PG8_BAR; PG8_MMA(0, 0, At, B0); PG8_MMA(0, 1, At, B1); PG8_BAR; PG8_SCHED;
;             PG8_LDA(At, 1, 1); PG8_STAGE(PG8_SB(1, 0), b3, voffB); PG8_STAGE(PG8_SB(1, 1), b3 + hstep, voffB);
;             PG8_WAIT_V(6); PG8_WAIT_L(0); PG8_BAR; PG8_MMA(1, 0, At, B0); PG8_MMA(1, 1, At, B1); PG8_BAR; PG8_SCHED;
.LBB0_763:
	ds_read_b128 v[154:157], v151
	ds_read_b128 v[158:161], v151 offset:1024
	ds_read_b128 v[162:165], v151 offset:2048
	ds_read_b128 v[166:169], v151 offset:3072
	ds_read_b128 v[170:173], v152
	ds_read_b128 v[174:177], v152 offset:1024
	ds_read_b128 v[178:181], v152 offset:2048
	ds_read_b128 v[182:185], v152 offset:3072
	s_add_u32 s34, s28, s30
	s_addc_u32 s35, s29, s31
	s_add_u32 s36, s34, 0x100
	s_addc_u32 s37, s35, 0
	s_add_u32 s34, s51, s30
	s_addc_u32 s35, s68, s31
	s_cmpk_eq_i32 s30, 0xf00
	s_cselect_b32 s35, s19, s35
	s_cselect_b32 s34, s49, s34
	s_cselect_b32 s37, s21, s37
	s_cselect_b32 s36, s48, s36
	v_lshl_add_u64 v[220:221], v[146:147], 0, s[30:31]
	v_lshl_add_u64 v[222:223], v[220:221], 0, s[8:9]
	s_add_i32 m0, s27, 0x8000
	ds_read_b128 v[188:191], v153
	ds_read_b128 v[192:195], v153 offset:1024
	ds_read_b128 v[196:199], v153 offset:2048
	ds_read_b128 v[200:203], v153 offset:3072
	ds_read_b128 v[204:207], v153 offset:4096
	ds_read_b128 v[208:211], v153 offset:5120
	ds_read_b128 v[212:215], v153 offset:6144
	ds_read_b128 v[216:219], v153 offset:7168
	global_load_lds_dwordx4 v[222:223], off
	v_lshl_add_u64 v[222:223], v[144:145], 0, s[30:31]
	v_lshl_add_u64 v[224:225], v[222:223], 0, s[8:9]
	s_add_i32 m0, s27, 0xa000
	v_lshl_add_u64 v[220:221], v[220:221], 0, s[14:15]
	global_load_lds_dwordx4 v[224:225], off
	s_add_i32 m0, s27, 0xc000
	s_nop 0
	global_load_lds_dwordx4 v[220:221], off
	v_lshl_add_u64 v[220:221], v[222:223], 0, s[14:15]
	s_add_i32 m0, s27, 0xe000
	s_nop 0
	global_load_lds_dwordx4 v[220:221], off
	s_waitcnt vmcnt(8)
	s_waitcnt lgkmcnt(0)
	s_barrier
	s_setprio 3
	s_waitcnt lgkmcnt(0)
	v_mfma_f32_16x16x32_bf16 v[124:127], v[154:157], v[188:191], v[124:127]
	v_mfma_f32_16x16x32_bf16 v[120:123], v[162:165], v[188:191], v[120:123]
	v_mfma_f32_16x16x32_bf16 v[108:111], v[154:157], v[196:199], v[108:111]
	v_mfma_f32_16x16x32_bf16 v[104:107], v[162:165], v[196:199], v[104:107]
	v_mfma_f32_16x16x32_bf16 v[92:95], v[154:157], v[204:207], v[92:95]
	v_mfma_f32_16x16x32_bf16 v[88:91], v[162:165], v[204:207], v[88:91]
	v_mfma_f32_16x16x32_bf16 v[76:79], v[154:157], v[212:215], v[76:79]
	v_mfma_f32_16x16x32_bf16 v[72:75], v[162:165], v[212:215], v[72:75]
	v_mfma_f32_16x16x32_bf16 v[124:127], v[158:161], v[192:195], v[124:127]
	v_mfma_f32_16x16x32_bf16 v[120:123], v[166:169], v[192:195], v[120:123]
	v_mfma_f32_16x16x32_bf16 v[108:111], v[158:161], v[200:203], v[108:111]
	v_mfma_f32_16x16x32_bf16 v[104:107], v[166:169], v[200:203], v[104:107]
	v_mfma_f32_16x16x32_bf16 v[92:95], v[158:161], v[208:211], v[92:95]
	v_mfma_f32_16x16x32_bf16 v[88:91], v[166:169], v[208:211], v[88:91]
	v_mfma_f32_16x16x32_bf16 v[76:79], v[158:161], v[216:219], v[76:79]
	v_mfma_f32_16x16x32_bf16 v[72:75], v[166:169], v[216:219], v[72:75]
	s_setprio 0
	s_setprio 3
	v_mfma_f32_16x16x32_bf16 v[116:119], v[170:173], v[188:191], v[116:119]
	v_mfma_f32_16x16x32_bf16 v[112:115], v[178:181], v[188:191], v[112:115]
	v_mfma_f32_16x16x32_bf16 v[100:103], v[170:173], v[196:199], v[100:103]
	v_mfma_f32_16x16x32_bf16 v[96:99], v[178:181], v[196:199], v[96:99]
	v_mfma_f32_16x16x32_bf16 v[84:87], v[170:173], v[204:207], v[84:87]
	v_mfma_f32_16x16x32_bf16 v[80:83], v[178:181], v[204:207], v[80:83]
	v_mfma_f32_16x16x32_bf16 v[68:71], v[170:173], v[212:215], v[68:71]
	v_mfma_f32_16x16x32_bf16 v[64:67], v[178:181], v[212:215], v[64:67]
	v_mfma_f32_16x16x32_bf16 v[116:119], v[174:177], v[192:195], v[116:119]
	v_mfma_f32_16x16x32_bf16 v[112:115], v[182:185], v[192:195], v[112:115]
	v_mfma_f32_16x16x32_bf16 v[100:103], v[174:177], v[200:203], v[100:103]
	v_mfma_f32_16x16x32_bf16 v[96:99], v[182:185], v[200:203], v[96:99]
	v_mfma_f32_16x16x32_bf16 v[84:87], v[174:177], v[208:211], v[84:87]
	v_mfma_f32_16x16x32_bf16 v[80:83], v[182:185], v[208:211], v[80:83]
	v_mfma_f32_16x16x32_bf16 v[68:71], v[174:177], v[216:219], v[68:71]
	v_mfma_f32_16x16x32_bf16 v[64:67], v[182:185], v[216:219], v[64:67]
	s_setprio 0
	s_barrier
	s_add_i32 s70, s44, s38
	v_lshl_add_u64 v[220:221], s[34:35], 0, v[132:133]
	s_mov_b32 m0, s70
	ds_read_b128 v[188:191], v153 offset:16384
	ds_read_b128 v[192:195], v153 offset:17408
	ds_read_b128 v[196:199], v153 offset:18432
	ds_read_b128 v[200:203], v153 offset:19456
	ds_read_b128 v[204:207], v153 offset:20480
	ds_read_b128 v[208:211], v153 offset:21504
	ds_read_b128 v[212:215], v153 offset:22528
	ds_read_b128 v[216:219], v153 offset:23552
	global_load_lds_dwordx4 v[220:221], off
	s_add_i32 m0, s70, 0x2000
	s_add_u32 s70, s34, 0x80000
	v_lshl_add_u64 v[222:223], s[34:35], 0, v[128:129]
	s_addc_u32 s71, s35, 0
	s_add_i32 s72, s45, s38
	global_load_lds_dwordx4 v[222:223], off
	v_lshl_add_u64 v[224:225], s[70:71], 0, v[132:133]
	s_mov_b32 m0, s72
	s_nop 0
	global_load_lds_dwordx4 v[224:225], off
	v_lshl_add_u64 v[224:225], s[70:71], 0, v[128:129]
	s_add_i32 m0, s72, 0x2000
	s_nop 0
	global_load_lds_dwordx4 v[224:225], off
	s_waitcnt vmcnt(6)
	s_waitcnt lgkmcnt(0)
	s_barrier
; #define PG8_STAGE(bufoff, gbase, voff) do { _Pragma("unroll") for (int _i = 0; _i < 2; ++_i) \
;         __builtin_amdgcn_global_load_lds((const unsigned*)((const char*)(gbase) + (voff)[_i]), (LAS unsigned*)(lds + (bufoff) + ldsw + _i * 8192), 16, 0, 0); } while (0)
; #define PG8_LDA(dst, b, h) do { _Pragma("unroll") for (int m = 0; m < 4; ++m) _Pragma("unroll") for (int k = 0; k < 2; ++k) dst[m][k] = *(const LAS bf16x8*)(lds + PG8_SA(b, h) + aoff + m * 2048 + k * 1024); } while (0)
; #define PG8_LDB(dst, b, h) do { _Pragma("unroll") for (int n = 0; n < 2; ++n) _Pragma("unroll") for (int k = 0; k < 2; ++k) dst[n][k] = *(const LAS bf16x8*)(lds + PG8_SB(b, h) + boff + n * 2048 + k * 1024); } while (0)
; #define PG8_MMA(ai, bj, At, Bt) do { __builtin_amdgcn_s_setprio(3); _Pragma("unroll") for (int m = 0; m < 4; ++m) _Pragma("unroll") for (int n = 0; n < 2; ++n) _Pragma("unroll") for (int k = 0; k < 2; ++k) \
;         acc[ai][bj][m][n] = __builtin_amdgcn_mfma_f32_16x16x32_bf16(Bt[n][k], At[m][k], acc[ai][bj][m][n], 0, 0, 0); __builtin_amdgcn_s_setprio(0); } while (0)
; #define PG8_WAIT_V(n) asm volatile("s_waitcnt vmcnt(" #n ")" ::: "memory")
; #define PG8_WAIT_L(n) asm volatile("s_waitcnt lgkmcnt(" #n ")" ::: "memory")
; #define PG8_BAR __builtin_amdgcn_s_barrier()
; #define PG8_SCHED __builtin_amdgcn_sched_barrier(0)
; template <class Epi, class Sched>
; __device__ __forceinline__ void gemm_phase(LAS unsigned char* lds, const Gemm g, const Sched& S, const Epi& E, int tid_in) {
;     ...
;             PG8_WAIT_V(6); PG8_WAIT_L(0); PG8_BAR; PG8_MMA(1, 0, At, B0); PG8_MMA(1, 1, At, B1); PG8_BAR; PG8_SCHED;
;             PG8_LDB(B0, 1, 0); PG8_LDB(B1, 1, 1); PG8_SCHED; PG8_LDA(At, 1, 0); PG8_STAGE(PG8_SA(0, 0), a2, voffA); PG8_STAGE(PG8_SA(0, 1), a2 + hstep, voffA);
;             PG8_WAIT_V(8); PG8_WAIT_L(0); PG8_BAR; PG8_MMA(0, 0, At, B0); PG8_MMA(0, 1, At, B1); PG8_BAR; PG8_SCHED;
	s_setprio 3
	s_waitcnt lgkmcnt(0)
	v_mfma_f32_16x16x32_bf16 v[60:63], v[154:157], v[188:191], v[60:63]
	v_mfma_f32_16x16x32_bf16 v[56:59], v[162:165], v[188:191], v[56:59]
	v_mfma_f32_16x16x32_bf16 v[44:47], v[154:157], v[196:199], v[44:47]
	v_mfma_f32_16x16x32_bf16 v[40:43], v[162:165], v[196:199], v[40:43]
	v_mfma_f32_16x16x32_bf16 v[28:31], v[154:157], v[204:207], v[28:31]
	v_mfma_f32_16x16x32_bf16 v[24:27], v[162:165], v[204:207], v[24:27]
	v_mfma_f32_16x16x32_bf16 v[12:15], v[154:157], v[212:215], v[12:15]
	v_mfma_f32_16x16x32_bf16 v[8:11], v[162:165], v[212:215], v[8:11]
	v_mfma_f32_16x16x32_bf16 v[60:63], v[158:161], v[192:195], v[60:63]
	v_mfma_f32_16x16x32_bf16 v[56:59], v[166:169], v[192:195], v[56:59]
	v_mfma_f32_16x16x32_bf16 v[44:47], v[158:161], v[200:203], v[44:47]
	v_mfma_f32_16x16x32_bf16 v[40:43], v[166:169], v[200:203], v[40:43]
	v_mfma_f32_16x16x32_bf16 v[28:31], v[158:161], v[208:211], v[28:31]
	v_mfma_f32_16x16x32_bf16 v[24:27], v[166:169], v[208:211], v[24:27]
	v_mfma_f32_16x16x32_bf16 v[12:15], v[158:161], v[216:219], v[12:15]
	v_mfma_f32_16x16x32_bf16 v[8:11], v[166:169], v[216:219], v[8:11]
	s_setprio 0
	s_setprio 3
	v_mfma_f32_16x16x32_bf16 v[52:55], v[170:173], v[188:191], v[52:55]
	v_mfma_f32_16x16x32_bf16 v[48:51], v[178:181], v[188:191], v[48:51]
	v_mfma_f32_16x16x32_bf16 v[36:39], v[170:173], v[196:199], v[36:39]
	v_mfma_f32_16x16x32_bf16 v[32:35], v[178:181], v[196:199], v[32:35]
	v_mfma_f32_16x16x32_bf16 v[20:23], v[170:173], v[204:207], v[20:23]
	v_mfma_f32_16x16x32_bf16 v[16:19], v[178:181], v[204:207], v[16:19]
	v_mfma_f32_16x16x32_bf16 v[4:7], v[170:173], v[212:215], v[4:7]
	v_mfma_f32_16x16x32_bf16 v[0:3], v[178:181], v[212:215], v[0:3]
	v_mfma_f32_16x16x32_bf16 v[52:55], v[174:177], v[192:195], v[52:55]
	v_mfma_f32_16x16x32_bf16 v[48:51], v[182:185], v[192:195], v[48:51]
	v_mfma_f32_16x16x32_bf16 v[36:39], v[174:177], v[200:203], v[36:39]
	v_mfma_f32_16x16x32_bf16 v[32:35], v[182:185], v[200:203], v[32:35]
	v_mfma_f32_16x16x32_bf16 v[20:23], v[174:177], v[208:211], v[20:23]
	v_mfma_f32_16x16x32_bf16 v[16:19], v[182:185], v[208:211], v[16:19]
	v_mfma_f32_16x16x32_bf16 v[4:7], v[174:177], v[216:219], v[4:7]
	v_mfma_f32_16x16x32_bf16 v[0:3], v[182:185], v[216:219], v[0:3]
	s_setprio 0
	s_barrier
	s_add_i32 s70, 0, 0x18000
	s_add_i32 s71, 0, 0x1c000
	v_add_u32_e32 v166, s70, v149
	v_add_u32_e32 v182, s71, v149
	ds_read_b128 v[154:157], v166
	ds_read_b128 v[158:161], v166 offset:1024
	ds_read_b128 v[162:165], v166 offset:2048
	ds_read_b128 v[166:169], v166 offset:3072
	ds_read_b128 v[170:173], v182
	ds_read_b128 v[174:177], v182 offset:1024
	ds_read_b128 v[178:181], v182 offset:2048
	ds_read_b128 v[182:185], v182 offset:3072
	s_mov_b32 m0, s27
	v_lshl_add_u64 v[224:225], s[36:37], 0, v[134:135]
	ds_read_b128 v[188:191], v153 offset:32768
	ds_read_b128 v[192:195], v153 offset:33792
	ds_read_b128 v[196:199], v153 offset:34816
	ds_read_b128 v[200:203], v153 offset:35840
	ds_read_b128 v[204:207], v153 offset:36864
	ds_read_b128 v[208:211], v153 offset:37888
	ds_read_b128 v[212:215], v153 offset:38912
	ds_read_b128 v[216:219], v153 offset:39936
	global_load_lds_dwordx4 v[224:225], off
	v_lshl_add_u64 v[224:225], s[36:37], 0, v[130:131]
	s_add_u32 s36, s36, 0x80000
	s_mov_b32 m0, s40
	s_addc_u32 s37, s37, 0
	global_load_lds_dwordx4 v[224:225], off
	v_lshl_add_u64 v[224:225], s[36:37], 0, v[134:135]
	s_mov_b32 m0, s41
	s_nop 0
	global_load_lds_dwordx4 v[224:225], off
	v_lshl_add_u64 v[224:225], s[36:37], 0, v[130:131]
	s_mov_b32 m0, s42
	s_nop 0
	global_load_lds_dwordx4 v[224:225], off
	s_waitcnt vmcnt(8)
	s_waitcnt lgkmcnt(0)
	s_barrier
	s_setprio 3
	s_waitcnt lgkmcnt(0)
	v_mfma_f32_16x16x32_bf16 v[124:127], v[154:157], v[188:191], v[124:127]
	v_mfma_f32_16x16x32_bf16 v[120:123], v[162:165], v[188:191], v[120:123]
	v_mfma_f32_16x16x32_bf16 v[108:111], v[154:157], v[196:199], v[108:111]
	v_mfma_f32_16x16x32_bf16 v[104:107], v[162:165], v[196:199], v[104:107]
	v_mfma_f32_16x16x32_bf16 v[92:95], v[154:157], v[204:207], v[92:95]
	v_mfma_f32_16x16x32_bf16 v[88:91], v[162:165], v[204:207], v[88:91]
	v_mfma_f32_16x16x32_bf16 v[76:79], v[154:157], v[212:215], v[76:79]
	v_mfma_f32_16x16x32_bf16 v[72:75], v[162:165], v[212:215], v[72:75]
	v_mfma_f32_16x16x32_bf16 v[124:127], v[158:161], v[192:195], v[124:127]
	v_mfma_f32_16x16x32_bf16 v[120:123], v[166:169], v[192:195], v[120:123]
	v_mfma_f32_16x16x32_bf16 v[108:111], v[158:161], v[200:203], v[108:111]
	v_mfma_f32_16x16x32_bf16 v[104:107], v[166:169], v[200:203], v[104:107]
	v_mfma_f32_16x16x32_bf16 v[92:95], v[158:161], v[208:211], v[92:95]
	v_mfma_f32_16x16x32_bf16 v[88:91], v[166:169], v[208:211], v[88:91]
	v_mfma_f32_16x16x32_bf16 v[76:79], v[158:161], v[216:219], v[76:79]
	v_mfma_f32_16x16x32_bf16 v[72:75], v[166:169], v[216:219], v[72:75]
	s_setprio 0
	s_setprio 3
	v_mfma_f32_16x16x32_bf16 v[116:119], v[170:173], v[188:191], v[116:119]
	v_mfma_f32_16x16x32_bf16 v[112:115], v[178:181], v[188:191], v[112:115]
	v_mfma_f32_16x16x32_bf16 v[100:103], v[170:173], v[196:199], v[100:103]
	v_mfma_f32_16x16x32_bf16 v[96:99], v[178:181], v[196:199], v[96:99]
	v_mfma_f32_16x16x32_bf16 v[84:87], v[170:173], v[204:207], v[84:87]
	v_mfma_f32_16x16x32_bf16 v[80:83], v[178:181], v[204:207], v[80:83]
	v_mfma_f32_16x16x32_bf16 v[68:71], v[170:173], v[212:215], v[68:71]
	v_mfma_f32_16x16x32_bf16 v[64:67], v[178:181], v[212:215], v[64:67]
	v_mfma_f32_16x16x32_bf16 v[116:119], v[174:177], v[192:195], v[116:119]
	v_mfma_f32_16x16x32_bf16 v[112:115], v[182:185], v[192:195], v[112:115]
	v_mfma_f32_16x16x32_bf16 v[100:103], v[174:177], v[200:203], v[100:103]
	v_mfma_f32_16x16x32_bf16 v[96:99], v[182:185], v[200:203], v[96:99]
	v_mfma_f32_16x16x32_bf16 v[84:87], v[174:177], v[208:211], v[84:87]
	v_mfma_f32_16x16x32_bf16 v[80:83], v[182:185], v[208:211], v[80:83]
	v_mfma_f32_16x16x32_bf16 v[68:71], v[174:177], v[216:219], v[68:71]
	v_mfma_f32_16x16x32_bf16 v[64:67], v[182:185], v[216:219], v[64:67]
	s_setprio 0
	s_barrier
; __device__ __forceinline__ float sigmoidf_(float x) { return __builtin_amdgcn_rcpf(1.0f + __expf(-x)); }
; __device__ __forceinline__ u32x4 pack8(f32x4 a, f32x4 b) { u32x4 w; w.x = cvt_pk_bf16(a[0], a[1]); w.y = cvt_pk_bf16(a[2], a[3]); w.z = cvt_pk_bf16(b[0], b[1]); w.w = cvt_pk_bf16(b[2], b[3]); return w; }
; #define PG8_STAGE(bufoff, gbase, voff) do { _Pragma("unroll") for (int _i = 0; _i < 2; ++_i) \
;         __builtin_amdgcn_global_load_lds((const unsigned*)((const char*)(gbase) + (voff)[_i]), (LAS unsigned*)(lds + (bufoff) + ldsw + _i * 8192), 16, 0, 0); } while (0)
; #define PG8_LDA(dst, b, h) do { _Pragma("unroll") for (int m = 0; m < 4; ++m) _Pragma("unroll") for (int k = 0; k < 2; ++k) dst[m][k] = *(const LAS bf16x8*)(lds + PG8_SA(b, h) + aoff + m * 2048 + k * 1024); } while (0)
; #define PG8_MMA(ai, bj, At, Bt) do { __builtin_amdgcn_s_setprio(3); _Pragma("unroll") for (int m = 0; m < 4; ++m) _Pragma("unroll") for (int n = 0; n < 2; ++n) _Pragma("unroll") for (int k = 0; k < 2; ++k) \
;         acc[ai][bj][m][n] = __builtin_amdgcn_mfma_f32_16x16x32_bf16(Bt[n][k], At[m][k], acc[ai][bj][m][n], 0, 0, 0); __builtin_amdgcn_s_setprio(0); } while (0)
; #define PG8_WAIT_V(n) asm volatile("s_waitcnt vmcnt(" #n ")" ::: "memory")
; template <class Epi, class Sched>
; __device__ __forceinline__ void gemm_phase(LAS unsigned char* lds, const Gemm g, const Sched& S, const Epi& E, int tid_in) {
;     ...
;             PG8_LDA(At, 1, 1); PG8_STAGE(PG8_SB(1, 0), b3, voffB); PG8_STAGE(PG8_SB(1, 1), b3 + hstep, voffB);
;             PG8_WAIT_V(6); PG8_WAIT_L(0); PG8_BAR; PG8_MMA(1, 0, At, B0); PG8_MMA(1, 1, At, B1); PG8_BAR; PG8_SCHED;
;         }
;         if (wr == 0) PG8_BAR;
;     __device__ __forceinline__ bool operator()(f32x4 (&acc)[2][2][4][2], const Unit& u, int wr, int wc, int fr, int fq) const {
;         const int row0 = u.pm * BM + wr * 64 + fr, col0 = u.pn * HALF + wc * 32 + 8 * fq;
; #pragma unroll
;         for (int ai = 0; ai < 2; ++ai)
; #pragma unroll
;             for (int m = 0; m < 4; ++m) {
;                 f32x4 v[2];
; #pragma unroll
;                 for (int n = 0; n < 2; ++n)
; #pragma unroll
;                     for (int i = 0; i < 4; ++i) { const float gx = acc[ai][0][m][n][i]; v[n][i] = gx * sigmoidf_(gx) * acc[ai][1][m][n][i]; }
;                 *(u32x4*)(O + (size_t)(row0 + ai * HALF + m * 16) * DFF + col0) = pack8(v[0], v[1]);
	s_add_i32 s36, s70, s38
	v_lshl_add_u64 v[220:221], v[220:221], 0, s[8:9]
	s_mov_b32 m0, s36
	ds_read_b128 v[188:191], v153 offset:49152
	ds_read_b128 v[192:195], v153 offset:50176
	ds_read_b128 v[196:199], v153 offset:51200
	ds_read_b128 v[200:203], v153 offset:52224
	ds_read_b128 v[204:207], v153 offset:53248
	ds_read_b128 v[208:211], v153 offset:54272
	ds_read_b128 v[212:215], v153 offset:55296
	ds_read_b128 v[216:219], v153 offset:56320
	global_load_lds_dwordx4 v[220:221], off
	s_add_i32 m0, s36, 0x2000
	s_add_u32 s34, s34, 0x80080
	v_lshl_add_u64 v[220:221], v[222:223], 0, s[8:9]
	s_addc_u32 s35, s35, 0
	s_add_i32 s36, s71, s38
	global_load_lds_dwordx4 v[220:221], off
	v_lshl_add_u64 v[220:221], s[34:35], 0, v[132:133]
	s_mov_b32 m0, s36
	s_nop 0
	global_load_lds_dwordx4 v[220:221], off
	v_lshl_add_u64 v[220:221], s[34:35], 0, v[128:129]
	s_add_i32 m0, s36, 0x2000
	s_nop 0
	global_load_lds_dwordx4 v[220:221], off
	s_waitcnt vmcnt(6)
	s_waitcnt lgkmcnt(0)
	s_barrier
	s_setprio 3
	s_waitcnt lgkmcnt(0)
	v_mfma_f32_16x16x32_bf16 v[60:63], v[154:157], v[188:191], v[60:63]
	v_mfma_f32_16x16x32_bf16 v[56:59], v[162:165], v[188:191], v[56:59]
	v_mfma_f32_16x16x32_bf16 v[44:47], v[154:157], v[196:199], v[44:47]
	v_mfma_f32_16x16x32_bf16 v[40:43], v[162:165], v[196:199], v[40:43]
	v_mfma_f32_16x16x32_bf16 v[28:31], v[154:157], v[204:207], v[28:31]
	v_mfma_f32_16x16x32_bf16 v[24:27], v[162:165], v[204:207], v[24:27]
	v_mfma_f32_16x16x32_bf16 v[12:15], v[154:157], v[212:215], v[12:15]
	v_mfma_f32_16x16x32_bf16 v[8:11], v[162:165], v[212:215], v[8:11]
	v_mfma_f32_16x16x32_bf16 v[60:63], v[158:161], v[192:195], v[60:63]
	v_mfma_f32_16x16x32_bf16 v[56:59], v[166:169], v[192:195], v[56:59]
	v_mfma_f32_16x16x32_bf16 v[44:47], v[158:161], v[200:203], v[44:47]
	v_mfma_f32_16x16x32_bf16 v[40:43], v[166:169], v[200:203], v[40:43]
	v_mfma_f32_16x16x32_bf16 v[28:31], v[158:161], v[208:211], v[28:31]
	v_mfma_f32_16x16x32_bf16 v[24:27], v[166:169], v[208:211], v[24:27]
	v_mfma_f32_16x16x32_bf16 v[12:15], v[158:161], v[216:219], v[12:15]
	v_mfma_f32_16x16x32_bf16 v[8:11], v[166:169], v[216:219], v[8:11]
	s_setprio 0
	s_setprio 3
	v_mfma_f32_16x16x32_bf16 v[52:55], v[170:173], v[188:191], v[52:55]
	v_mfma_f32_16x16x32_bf16 v[48:51], v[178:181], v[188:191], v[48:51]
	v_mfma_f32_16x16x32_bf16 v[36:39], v[170:173], v[196:199], v[36:39]
	v_mfma_f32_16x16x32_bf16 v[32:35], v[178:181], v[196:199], v[32:35]
	v_mfma_f32_16x16x32_bf16 v[20:23], v[170:173], v[204:207], v[20:23]
	v_mfma_f32_16x16x32_bf16 v[16:19], v[178:181], v[204:207], v[16:19]
	v_mfma_f32_16x16x32_bf16 v[4:7], v[170:173], v[212:215], v[4:7]
	v_mfma_f32_16x16x32_bf16 v[0:3], v[178:181], v[212:215], v[0:3]
	v_mfma_f32_16x16x32_bf16 v[52:55], v[174:177], v[192:195], v[52:55]
	v_mfma_f32_16x16x32_bf16 v[48:51], v[182:185], v[192:195], v[48:51]
	v_mfma_f32_16x16x32_bf16 v[36:39], v[174:177], v[200:203], v[36:39]
	v_mfma_f32_16x16x32_bf16 v[32:35], v[182:185], v[200:203], v[32:35]
	v_mfma_f32_16x16x32_bf16 v[20:23], v[174:177], v[208:211], v[20:23]
	v_mfma_f32_16x16x32_bf16 v[16:19], v[182:185], v[208:211], v[16:19]
	v_mfma_f32_16x16x32_bf16 v[4:7], v[174:177], v[216:219], v[4:7]
	v_mfma_f32_16x16x32_bf16 v[0:3], v[182:185], v[216:219], v[0:3]
	s_setprio 0
	s_barrier
	s_add_i32 s69, s69, 2
	s_add_u32 s30, s30, 0x100
	s_addc_u32 s31, s31, 0
	s_cmp_gt_u32 s69, 29
	s_cbranch_scc0 .LBB0_763
	s_andn2_b64 vcc, s[16:17], s[4:5]
	s_cbranch_vccz .LBB0_766
	s_barrier
.LBB0_766:
	v_mul_f32_e32 v145, 0xbfb8aa3b, v124
	v_exp_f32_e32 v145, v145
	v_mul_f32_e32 v146, 0xbfb8aa3b, v125
	v_exp_f32_e32 v147, v146
	v_lshl_or_b32 v146, s47, 7, v150
	v_add_f32_e32 v145, 1.0, v145
	v_rcp_f32_e32 v145, v145
	v_add_f32_e32 v147, 1.0, v147
	v_rcp_f32_e32 v154, v147
	v_lshl_add_u32 v144, s26, 8, v148
	v_mul_f32_e32 v124, v124, v145
	v_mul_f32_e32 v116, v124, v116
	v_mul_f32_e32 v124, v125, v154
	v_mul_f32_e32 v125, 0xbfb8aa3b, v126
	v_exp_f32_e32 v125, v125
	v_mul_f32_e32 v145, 0xbfb8aa3b, v127
	v_exp_f32_e32 v145, v145
	v_mul_f32_e32 v117, v124, v117
	v_add_f32_e32 v124, 1.0, v125
	v_rcp_f32_e32 v124, v124
	v_add_f32_e32 v125, 1.0, v145
	v_mul_f32_e32 v145, 0xbfb8aa3b, v120
	v_rcp_f32_e32 v125, v125
	v_exp_f32_e32 v145, v145
	v_mul_f32_e32 v124, v126, v124
	v_mul_f32_e32 v118, v124, v118
	v_mul_f32_e32 v124, v127, v125
	v_add_f32_e32 v125, 1.0, v145
	v_rcp_f32_e32 v125, v125
	v_mul_f32_e32 v126, 0xbfb8aa3b, v121
	v_exp_f32_e32 v126, v126
	v_mul_f32_e32 v119, v124, v119
	v_mul_f32_e32 v120, v120, v125
	v_mul_f32_e32 v112, v120, v112
	v_add_f32_e32 v120, 1.0, v126
	v_mul_f32_e32 v124, 0xbfb8aa3b, v122
	v_rcp_f32_e32 v120, v120
	v_exp_f32_e32 v124, v124
	v_mul_f32_e32 v125, 0xbfb8aa3b, v123
	v_exp_f32_e32 v125, v125
	v_mul_f32_e32 v120, v121, v120
	v_add_f32_e32 v121, 1.0, v124
	v_rcp_f32_e32 v121, v121
	v_add_f32_e32 v124, 1.0, v125
	v_rcp_f32_e32 v124, v124
	v_mul_f32_e32 v113, v120, v113
	v_mul_f32_e32 v120, v122, v121
	v_mul_f32_e32 v122, 0xbfb8aa3b, v108
	v_mul_f32_e32 v114, v120, v114
	v_mul_f32_e32 v120, v123, v124
	v_exp_f32_e32 v122, v122
	v_mul_f32_e32 v123, 0xbfb8aa3b, v109
	v_exp_f32_e32 v123, v123
	v_ashrrev_i32_e32 v147, 31, v146
	v_add_f32_e32 v122, 1.0, v122
	v_rcp_f32_e32 v122, v122
	v_add_f32_e32 v123, 1.0, v123
	v_rcp_f32_e32 v123, v123
	v_mul_f32_e32 v115, v120, v115
	v_cvt_pk_bf16_f32 v116, v116, v117
	v_cvt_pk_bf16_f32 v117, v118, v119
	v_cvt_pk_bf16_f32 v118, v112, v113
	v_mov_b64_e32 v[112:113], s[12:13]
	v_cvt_pk_bf16_f32 v119, v114, v115
	v_mad_i64_i32 v[120:121], s[28:29], v144, s46, v[112:113]
	v_lshlrev_b64 v[114:115], 1, v[146:147]
	v_mul_f32_e32 v108, v108, v122
	v_lshl_add_u64 v[120:121], v[120:121], 0, v[114:115]
; __device__ __forceinline__ float sigmoidf_(float x) { return __builtin_amdgcn_rcpf(1.0f + __expf(-x)); }
; __device__ __forceinline__ u32x4 pack8(f32x4 a, f32x4 b) { u32x4 w; w.x = cvt_pk_bf16(a[0], a[1]); w.y = cvt_pk_bf16(a[2], a[3]); w.z = cvt_pk_bf16(b[0], b[1]); w.w = cvt_pk_bf16(b[2], b[3]); return w; }
;     __device__ __forceinline__ bool operator()(f32x4 (&acc)[2][2][4][2], const Unit& u, int wr, int wc, int fr, int fq) const {
;         const int row0 = u.pm * BM + wr * 64 + fr, col0 = u.pn * HALF + wc * 32 + 8 * fq;
; #pragma unroll
;         for (int ai = 0; ai < 2; ++ai)
; #pragma unroll
;             for (int m = 0; m < 4; ++m) {
;                 f32x4 v[2];
; #pragma unroll
;                 for (int n = 0; n < 2; ++n)
; #pragma unroll
;                     for (int i = 0; i < 4; ++i) { const float gx = acc[ai][0][m][n][i]; v[n][i] = gx * sigmoidf_(gx) * acc[ai][1][m][n][i]; }
;                 *(u32x4*)(O + (size_t)(row0 + ai * HALF + m * 16) * DFF + col0) = pack8(v[0], v[1]);
	v_mul_f32_e32 v100, v108, v100
	v_mul_f32_e32 v108, v109, v123
	v_mul_f32_e32 v109, 0xbfb8aa3b, v110
	global_store_dwordx4 v[120:121], v[116:119], off
	v_exp_f32_e32 v109, v109
	v_mul_f32_e32 v101, v108, v101
	v_mul_f32_e32 v116, 0xbfb8aa3b, v111
	v_exp_f32_e32 v116, v116
	v_add_f32_e32 v108, 1.0, v109
	v_rcp_f32_e32 v108, v108
	s_andn2_b64 vcc, exec, s[4:5]
	v_add_f32_e32 v109, 1.0, v116
	v_mul_f32_e32 v116, 0xbfb8aa3b, v104
	v_rcp_f32_e32 v109, v109
	v_exp_f32_e32 v116, v116
	v_mul_f32_e32 v108, v110, v108
	v_mul_f32_e32 v102, v108, v102
	v_mul_f32_e32 v108, v111, v109
	v_add_f32_e32 v109, 1.0, v116
	v_rcp_f32_e32 v109, v109
	v_mul_f32_e32 v110, 0xbfb8aa3b, v105
	v_exp_f32_e32 v110, v110
	v_mul_f32_e32 v103, v108, v103
	v_mul_f32_e32 v104, v104, v109
	v_mul_f32_e32 v104, v104, v96
	v_add_f32_e32 v96, 1.0, v110
	v_mul_f32_e32 v108, 0xbfb8aa3b, v106
	v_rcp_f32_e32 v96, v96
	v_exp_f32_e32 v108, v108
	v_mul_f32_e32 v109, 0xbfb8aa3b, v107
	v_exp_f32_e32 v109, v109
	v_mul_f32_e32 v96, v105, v96
	v_add_f32_e32 v105, 1.0, v108
	v_rcp_f32_e32 v105, v105
	v_add_f32_e32 v108, 1.0, v109
	v_rcp_f32_e32 v108, v108
	v_mul_f32_e32 v109, v96, v97
	v_mul_f32_e32 v96, v106, v105
	v_mul_f32_e32 v105, v96, v98
	v_mul_f32_e32 v96, v107, v108
	v_mul_f32_e32 v99, v96, v99
	v_cvt_pk_bf16_f32 v96, v100, v101
	v_cvt_pk_bf16_f32 v97, v102, v103
	v_mul_f32_e32 v102, 0xbfb8aa3b, v92
	v_exp_f32_e32 v102, v102
	v_mul_f32_e32 v103, 0xbfb8aa3b, v93
	v_exp_f32_e32 v103, v103
	v_or_b32_e32 v100, 16, v144
	v_add_f32_e32 v102, 1.0, v102
	v_rcp_f32_e32 v102, v102
	v_add_f32_e32 v103, 1.0, v103
	v_rcp_f32_e32 v103, v103
	v_mad_i64_i32 v[100:101], s[28:29], v100, s46, v[112:113]
	v_mul_f32_e32 v92, v92, v102
	v_lshl_add_u64 v[100:101], v[100:101], 0, v[114:115]
	v_mul_f32_e32 v84, v92, v84
	v_mul_f32_e32 v92, v93, v103
	v_mul_f32_e32 v93, 0xbfb8aa3b, v94
	v_cvt_pk_bf16_f32 v98, v104, v109
	v_cvt_pk_bf16_f32 v99, v105, v99
	global_store_dwordx4 v[100:101], v[96:99], off
	v_exp_f32_e32 v93, v93
	v_mul_f32_e32 v85, v92, v85
	v_mul_f32_e32 v96, 0xbfb8aa3b, v95
	v_exp_f32_e32 v96, v96
	v_add_f32_e32 v92, 1.0, v93
	v_rcp_f32_e32 v92, v92
	s_mov_b64 s[4:5], -1
	v_add_f32_e32 v93, 1.0, v96
	v_mul_f32_e32 v96, 0xbfb8aa3b, v88
	v_rcp_f32_e32 v93, v93
	v_exp_f32_e32 v96, v96
	v_mul_f32_e32 v92, v94, v92
	v_mul_f32_e32 v86, v92, v86
	v_mul_f32_e32 v92, v95, v93
	v_add_f32_e32 v93, 1.0, v96
	v_rcp_f32_e32 v93, v93
	v_mul_f32_e32 v94, 0xbfb8aa3b, v89
	v_exp_f32_e32 v94, v94
	v_mul_f32_e32 v87, v92, v87
	v_mul_f32_e32 v88, v88, v93
	v_mul_f32_e32 v88, v88, v80
	v_add_f32_e32 v80, 1.0, v94
	v_mul_f32_e32 v92, 0xbfb8aa3b, v90
	v_rcp_f32_e32 v80, v80
	v_exp_f32_e32 v92, v92
	v_mul_f32_e32 v93, 0xbfb8aa3b, v91
	v_exp_f32_e32 v93, v93
	v_mul_f32_e32 v80, v89, v80
	v_add_f32_e32 v89, 1.0, v92
	v_rcp_f32_e32 v89, v89
	v_add_f32_e32 v92, 1.0, v93
	v_rcp_f32_e32 v92, v92
	v_mul_f32_e32 v93, v80, v81
	v_mul_f32_e32 v80, v90, v89
	v_mul_f32_e32 v89, v80, v82
	v_mul_f32_e32 v80, v91, v92
	v_mul_f32_e32 v83, v80, v83
	v_cvt_pk_bf16_f32 v80, v84, v85
	v_cvt_pk_bf16_f32 v81, v86, v87
	v_mul_f32_e32 v86, 0xbfb8aa3b, v76
	v_exp_f32_e32 v86, v86
	v_mul_f32_e32 v87, 0xbfb8aa3b, v77
	v_exp_f32_e32 v87, v87
	v_or_b32_e32 v84, 32, v144
	v_add_f32_e32 v86, 1.0, v86
	v_rcp_f32_e32 v86, v86
	v_add_f32_e32 v87, 1.0, v87
	v_rcp_f32_e32 v87, v87
	v_mad_i64_i32 v[84:85], s[28:29], v84, s46, v[112:113]
	v_mul_f32_e32 v76, v76, v86
	v_lshl_add_u64 v[84:85], v[84:85], 0, v[114:115]
	v_mul_f32_e32 v68, v76, v68
	v_mul_f32_e32 v76, v77, v87
	v_mul_f32_e32 v77, 0xbfb8aa3b, v78
	v_cvt_pk_bf16_f32 v82, v88, v93
	v_cvt_pk_bf16_f32 v83, v89, v83
	global_store_dwordx4 v[84:85], v[80:83], off
	v_exp_f32_e32 v77, v77
	v_mul_f32_e32 v69, v76, v69
	v_mul_f32_e32 v80, 0xbfb8aa3b, v79
	v_exp_f32_e32 v80, v80
	v_add_f32_e32 v76, 1.0, v77
	v_rcp_f32_e32 v76, v76
	v_add_f32_e32 v77, 1.0, v80
	v_mul_f32_e32 v80, 0xbfb8aa3b, v72
	v_rcp_f32_e32 v77, v77
	v_exp_f32_e32 v80, v80
	v_mul_f32_e32 v76, v78, v76
	v_mul_f32_e32 v70, v76, v70
	v_mul_f32_e32 v76, v79, v77
	v_add_f32_e32 v77, 1.0, v80
	v_rcp_f32_e32 v77, v77
	v_mul_f32_e32 v78, 0xbfb8aa3b, v73
	v_exp_f32_e32 v78, v78
	v_mul_f32_e32 v71, v76, v71
	v_mul_f32_e32 v72, v72, v77
	v_mul_f32_e32 v72, v72, v64
	v_add_f32_e32 v64, 1.0, v78
	v_mul_f32_e32 v76, 0xbfb8aa3b, v74
	v_rcp_f32_e32 v64, v64
	v_exp_f32_e32 v76, v76
	v_mul_f32_e32 v77, 0xbfb8aa3b, v75
	v_exp_f32_e32 v77, v77
	v_mul_f32_e32 v64, v73, v64
	v_add_f32_e32 v73, 1.0, v76
	v_rcp_f32_e32 v73, v73
	v_add_f32_e32 v76, 1.0, v77
	v_rcp_f32_e32 v76, v76
	v_mul_f32_e32 v77, v64, v65
	v_mul_f32_e32 v64, v74, v73
	v_mul_f32_e32 v73, v64, v66
	v_mul_f32_e32 v64, v75, v76
	v_mul_f32_e32 v67, v64, v67
	v_cvt_pk_bf16_f32 v64, v68, v69
	v_cvt_pk_bf16_f32 v65, v70, v71
	v_mul_f32_e32 v70, 0xbfb8aa3b, v60
	v_exp_f32_e32 v70, v70
	v_mul_f32_e32 v71, 0xbfb8aa3b, v61
	v_or_b32_e32 v68, 48, v144
	v_exp_f32_e32 v71, v71
	v_mad_i64_i32 v[68:69], s[28:29], v68, s46, v[112:113]
	v_lshl_add_u64 v[68:69], v[68:69], 0, v[114:115]
	v_cvt_pk_bf16_f32 v66, v72, v77
	v_cvt_pk_bf16_f32 v67, v73, v67
	global_store_dwordx4 v[68:69], v[64:67], off
	s_nop 1
	v_add_f32_e32 v64, 1.0, v70
	v_rcp_f32_e32 v64, v64
	v_add_f32_e32 v65, 1.0, v71
	v_rcp_f32_e32 v65, v65
	v_add_u32_e32 v66, 0x80, v144
	v_mul_f32_e32 v60, v60, v64
	v_mul_f32_e32 v52, v60, v52
	v_mul_f32_e32 v60, v61, v65
	v_mul_f32_e32 v61, 0xbfb8aa3b, v62
	v_exp_f32_e32 v61, v61
	v_mul_f32_e32 v64, 0xbfb8aa3b, v63
	v_exp_f32_e32 v64, v64
	v_mul_f32_e32 v53, v60, v53
	v_add_f32_e32 v60, 1.0, v61
	v_rcp_f32_e32 v60, v60
	v_add_f32_e32 v61, 1.0, v64
	v_mul_f32_e32 v64, 0xbfb8aa3b, v56
	v_rcp_f32_e32 v61, v61
; __device__ __forceinline__ float sigmoidf_(float x) { return __builtin_amdgcn_rcpf(1.0f + __expf(-x)); }
; __device__ __forceinline__ u32x4 pack8(f32x4 a, f32x4 b) { u32x4 w; w.x = cvt_pk_bf16(a[0], a[1]); w.y = cvt_pk_bf16(a[2], a[3]); w.z = cvt_pk_bf16(b[0], b[1]); w.w = cvt_pk_bf16(b[2], b[3]); return w; }
; #define PG8_BAR __builtin_amdgcn_s_barrier()
; template <class Epi, class Sched>
; __device__ __forceinline__ void gemm_phase(LAS unsigned char* lds, const Gemm g, const Sched& S, const Epi& E, int tid_in) {
;     ...
;         if (!has_next) break;
;         if (!keep) {
; #pragma unroll
;             for (int a = 0; a < 2; ++a)
; #pragma unroll
;                 for (int b = 0; b < 2; ++b)
; #pragma unroll
;                     for (int m = 0; m < 4; ++m)
; #pragma unroll
;                         for (int n = 0; n < 2; ++n) acc[a][b][m][n] = (f32x4){0.f, 0.f, 0.f, 0.f};
;         }
;         cur = nxt; cA = nA; cB = nB; ++ui;
;         if (wr == 1) PG8_BAR;
;     __device__ __forceinline__ bool operator()(f32x4 (&acc)[2][2][4][2], const Unit& u, int wr, int wc, int fr, int fq) const {
;     ...
;         for (int ai = 0; ai < 2; ++ai)
; #pragma unroll
;             for (int m = 0; m < 4; ++m) {
;                 f32x4 v[2];
; #pragma unroll
;                 for (int n = 0; n < 2; ++n)
; #pragma unroll
;                     for (int i = 0; i < 4; ++i) { const float gx = acc[ai][0][m][n][i]; v[n][i] = gx * sigmoidf_(gx) * acc[ai][1][m][n][i]; }
;                 *(u32x4*)(O + (size_t)(row0 + ai * HALF + m * 16) * DFF + col0) = pack8(v[0], v[1]);
	v_exp_f32_e32 v64, v64
	v_mul_f32_e32 v60, v62, v60
	v_mul_f32_e32 v54, v60, v54
	v_mul_f32_e32 v60, v63, v61
	v_add_f32_e32 v61, 1.0, v64
	v_rcp_f32_e32 v61, v61
	v_mul_f32_e32 v62, 0xbfb8aa3b, v57
	v_exp_f32_e32 v62, v62
	v_mul_f32_e32 v55, v60, v55
	v_mul_f32_e32 v56, v56, v61
	v_mul_f32_e32 v56, v56, v48
	v_add_f32_e32 v48, 1.0, v62
	v_mul_f32_e32 v60, 0xbfb8aa3b, v58
	v_rcp_f32_e32 v48, v48
	v_exp_f32_e32 v60, v60
	v_mul_f32_e32 v61, 0xbfb8aa3b, v59
	v_exp_f32_e32 v61, v61
	v_mul_f32_e32 v48, v57, v48
	v_add_f32_e32 v57, 1.0, v60
	v_rcp_f32_e32 v57, v57
	v_add_f32_e32 v60, 1.0, v61
	v_rcp_f32_e32 v60, v60
	v_mul_f32_e32 v61, v48, v49
	v_mul_f32_e32 v48, v58, v57
	v_mul_f32_e32 v57, v48, v50
	v_mul_f32_e32 v48, v59, v60
	v_mul_f32_e32 v51, v48, v51
	v_cvt_pk_bf16_f32 v48, v52, v53
	v_cvt_pk_bf16_f32 v49, v54, v55
	v_mul_f32_e32 v54, 0xbfb8aa3b, v44
	v_exp_f32_e32 v54, v54
	v_mul_f32_e32 v55, 0xbfb8aa3b, v45
	v_exp_f32_e32 v55, v55
	v_mad_i64_i32 v[52:53], s[28:29], v66, s46, v[112:113]
	v_add_f32_e32 v54, 1.0, v54
	v_rcp_f32_e32 v54, v54
	v_add_f32_e32 v55, 1.0, v55
	v_rcp_f32_e32 v55, v55
	v_lshl_add_u64 v[52:53], v[52:53], 0, v[114:115]
	v_mul_f32_e32 v44, v44, v54
	v_mul_f32_e32 v36, v44, v36
	v_mul_f32_e32 v44, v45, v55
	v_mul_f32_e32 v45, 0xbfb8aa3b, v46
	v_cvt_pk_bf16_f32 v50, v56, v61
	v_cvt_pk_bf16_f32 v51, v57, v51
	global_store_dwordx4 v[52:53], v[48:51], off
	v_exp_f32_e32 v45, v45
	v_mul_f32_e32 v37, v44, v37
	v_mul_f32_e32 v48, 0xbfb8aa3b, v47
	v_exp_f32_e32 v48, v48
	v_add_f32_e32 v44, 1.0, v45
	v_rcp_f32_e32 v44, v44
	v_add_f32_e32 v45, 1.0, v48
	v_mul_f32_e32 v48, 0xbfb8aa3b, v40
	v_rcp_f32_e32 v45, v45
	v_exp_f32_e32 v48, v48
	v_mul_f32_e32 v44, v46, v44
	v_mul_f32_e32 v38, v44, v38
	v_mul_f32_e32 v44, v47, v45
	v_add_f32_e32 v45, 1.0, v48
	v_rcp_f32_e32 v45, v45
	v_mul_f32_e32 v46, 0xbfb8aa3b, v41
	v_exp_f32_e32 v46, v46
	v_mul_f32_e32 v39, v44, v39
	v_mul_f32_e32 v40, v40, v45
	v_mul_f32_e32 v40, v40, v32
	v_add_f32_e32 v32, 1.0, v46
	v_mul_f32_e32 v44, 0xbfb8aa3b, v42
	v_rcp_f32_e32 v32, v32
	v_exp_f32_e32 v44, v44
	v_mul_f32_e32 v45, 0xbfb8aa3b, v43
	v_exp_f32_e32 v45, v45
	v_mul_f32_e32 v32, v41, v32
	v_add_f32_e32 v41, 1.0, v44
	v_rcp_f32_e32 v41, v41
	v_add_f32_e32 v44, 1.0, v45
	v_rcp_f32_e32 v44, v44
	v_mul_f32_e32 v45, v32, v33
	v_mul_f32_e32 v32, v42, v41
	v_mul_f32_e32 v41, v32, v34
	v_mul_f32_e32 v32, v43, v44
	v_mul_f32_e32 v35, v32, v35
	v_cvt_pk_bf16_f32 v32, v36, v37
	v_cvt_pk_bf16_f32 v33, v38, v39
	v_mul_f32_e32 v38, 0xbfb8aa3b, v28
	v_exp_f32_e32 v38, v38
	v_mul_f32_e32 v39, 0xbfb8aa3b, v29
	v_exp_f32_e32 v39, v39
	v_add_u32_e32 v36, 0x90, v144
	v_add_f32_e32 v38, 1.0, v38
	v_rcp_f32_e32 v38, v38
	v_add_f32_e32 v39, 1.0, v39
	v_rcp_f32_e32 v39, v39
	v_mad_i64_i32 v[36:37], s[28:29], v36, s46, v[112:113]
	v_mul_f32_e32 v28, v28, v38
	v_lshl_add_u64 v[36:37], v[36:37], 0, v[114:115]
	v_mul_f32_e32 v20, v28, v20
	v_mul_f32_e32 v28, v29, v39
	v_mul_f32_e32 v29, 0xbfb8aa3b, v30
	v_cvt_pk_bf16_f32 v34, v40, v45
	v_cvt_pk_bf16_f32 v35, v41, v35
	global_store_dwordx4 v[36:37], v[32:35], off
	v_exp_f32_e32 v29, v29
	v_mul_f32_e32 v21, v28, v21
	v_mul_f32_e32 v32, 0xbfb8aa3b, v31
	v_exp_f32_e32 v32, v32
	v_add_f32_e32 v28, 1.0, v29
	v_rcp_f32_e32 v28, v28
	v_add_f32_e32 v29, 1.0, v32
	v_mul_f32_e32 v32, 0xbfb8aa3b, v24
	v_rcp_f32_e32 v29, v29
	v_exp_f32_e32 v32, v32
	v_mul_f32_e32 v28, v30, v28
	v_mul_f32_e32 v22, v28, v22
	v_mul_f32_e32 v28, v31, v29
	v_add_f32_e32 v29, 1.0, v32
	v_rcp_f32_e32 v29, v29
	v_mul_f32_e32 v30, 0xbfb8aa3b, v25
	v_exp_f32_e32 v30, v30
	v_mul_f32_e32 v23, v28, v23
	v_mul_f32_e32 v24, v24, v29
	v_mul_f32_e32 v24, v24, v16
	v_add_f32_e32 v16, 1.0, v30
	v_mul_f32_e32 v28, 0xbfb8aa3b, v26
	v_rcp_f32_e32 v16, v16
	v_exp_f32_e32 v28, v28
	v_mul_f32_e32 v29, 0xbfb8aa3b, v27
	v_exp_f32_e32 v29, v29
	v_mul_f32_e32 v16, v25, v16
	v_add_f32_e32 v25, 1.0, v28
	v_rcp_f32_e32 v25, v25
	v_add_f32_e32 v28, 1.0, v29
	v_rcp_f32_e32 v28, v28
	v_mul_f32_e32 v29, v16, v17
	v_mul_f32_e32 v16, v26, v25
	v_mul_f32_e32 v25, v16, v18
	v_mul_f32_e32 v16, v27, v28
	v_mul_f32_e32 v19, v16, v19
	v_cvt_pk_bf16_f32 v16, v20, v21
	v_cvt_pk_bf16_f32 v17, v22, v23
	v_mul_f32_e32 v22, 0xbfb8aa3b, v12
	v_exp_f32_e32 v22, v22
	v_mul_f32_e32 v23, 0xbfb8aa3b, v13
	v_exp_f32_e32 v23, v23
	v_add_u32_e32 v20, 0xa0, v144
	v_add_f32_e32 v22, 1.0, v22
	v_rcp_f32_e32 v22, v22
	v_add_f32_e32 v23, 1.0, v23
	v_rcp_f32_e32 v23, v23
	v_mad_i64_i32 v[20:21], s[28:29], v20, s46, v[112:113]
	v_mul_f32_e32 v12, v12, v22
	v_lshl_add_u64 v[20:21], v[20:21], 0, v[114:115]
	v_mul_f32_e32 v4, v12, v4
	v_mul_f32_e32 v12, v13, v23
	v_mul_f32_e32 v13, 0xbfb8aa3b, v14
	v_cvt_pk_bf16_f32 v18, v24, v29
	v_cvt_pk_bf16_f32 v19, v25, v19
	global_store_dwordx4 v[20:21], v[16:19], off
	v_exp_f32_e32 v13, v13
	v_mul_f32_e32 v5, v12, v5
	v_mul_f32_e32 v16, 0xbfb8aa3b, v15
	v_exp_f32_e32 v16, v16
	v_add_f32_e32 v12, 1.0, v13
	v_rcp_f32_e32 v12, v12
	v_add_f32_e32 v13, 1.0, v16
	v_mul_f32_e32 v16, 0xbfb8aa3b, v8
	v_rcp_f32_e32 v13, v13
	v_exp_f32_e32 v16, v16
	v_mul_f32_e32 v12, v14, v12
	v_mul_f32_e32 v6, v12, v6
	v_mul_f32_e32 v12, v15, v13
	v_add_f32_e32 v13, 1.0, v16
	v_rcp_f32_e32 v13, v13
	v_mul_f32_e32 v14, 0xbfb8aa3b, v9
	v_exp_f32_e32 v14, v14
	v_mul_f32_e32 v7, v12, v7
	v_mul_f32_e32 v8, v8, v13
	v_mul_f32_e32 v8, v8, v0
	v_add_f32_e32 v0, 1.0, v14
	v_mul_f32_e32 v12, 0xbfb8aa3b, v10
	v_rcp_f32_e32 v0, v0
	v_exp_f32_e32 v12, v12
	v_mul_f32_e32 v13, 0xbfb8aa3b, v11
	v_exp_f32_e32 v13, v13
	v_mul_f32_e32 v0, v9, v0
	v_add_f32_e32 v9, 1.0, v12
	v_rcp_f32_e32 v9, v9
	v_add_f32_e32 v12, 1.0, v13
	v_rcp_f32_e32 v12, v12
	v_mul_f32_e32 v13, v0, v1
	v_mul_f32_e32 v0, v10, v9
	v_mul_f32_e32 v9, v0, v2
	v_mul_f32_e32 v0, v11, v12
	v_mul_f32_e32 v3, v0, v3
	v_cvt_pk_bf16_f32 v0, v4, v5
	v_add_u32_e32 v4, 0xb0, v144
	v_mad_i64_i32 v[4:5], s[28:29], v4, s46, v[112:113]
	v_lshl_add_u64 v[4:5], v[4:5], 0, v[114:115]
	v_cvt_pk_bf16_f32 v1, v6, v7
	v_cvt_pk_bf16_f32 v2, v8, v13
	v_cvt_pk_bf16_f32 v3, v9, v3
	global_store_dwordx4 v[4:5], v[0:3], off
	s_cbranch_vccnz .LBB0_759
	s_andn2_b64 vcc, exec, s[6:7]
	s_cbranch_vccnz .LBB0_758
	s_branch .LBB0_758
